# past: first-group list entries fetched behind K/V staging loads, its Q rows issued before the staging barrier
# speedup vs baseline: 1.0077x; 1.0077x over previous
.LBB0_254:
	s_and_b32 s0, s34, 11
	s_cmp_lg_u32 s0, 0
	s_cselect_b64 s[16:17], -1, 0
	s_cmp_lg_u32 s0, 3
	s_cselect_b64 s[18:19], -1, 0
	s_and_b64 s[16:17], s[16:17], s[18:19]
	s_cmp_lg_u32 s34, 8
	s_cselect_b64 s[18:19], -1, 0
	s_and_b64 s[16:17], s[18:19], s[16:17]
	s_add_i32 s0, s34, -13
	s_cmp_lt_u32 s0, -2
	s_cselect_b64 s[18:19], -1, 0
	s_and_b64 s[16:17], s[18:19], s[16:17]
	s_waitcnt vmcnt(3)
	v_cndmask_b32_e64 v0, 0, 1, s[16:17]
	v_cmp_ne_u32_e32 vcc, v0, v177
	s_cbranch_vccnz .LBB0_253
	s_lshl_b32 s0, s34, 15
	v_lshl_add_u64 v[24:25], v[152:153], 0, s[0:1]
	s_lshl_b32 s0, s34, 9
	v_mov_b32_e32 v133, v117
	v_lshl_add_u64 v[28:29], v[154:155], 0, s[0:1]
	v_lshl_add_u64 v[0:1], v[24:25], 0, v[132:133]
	v_mov_b32_e32 v135, v117
	s_barrier
	global_load_dwordx4 v[0:3], v[0:1], off
	s_waitcnt vmcnt(3)
	v_lshl_add_u64 v[4:5], v[28:29], 0, v[134:135]
	v_mov_b32_e32 v137, v117
	global_load_dwordx4 v[4:7], v[4:5], off
	s_waitcnt vmcnt(3)
	v_lshl_add_u64 v[8:9], v[24:25], 0, v[136:137]
	v_mov_b32_e32 v139, v117
	global_load_dwordx4 v[8:11], v[8:9], off
	s_waitcnt vmcnt(3)
	v_lshl_add_u64 v[12:13], v[28:29], 0, v[138:139]
	v_mov_b32_e32 v141, v117
	global_load_dwordx4 v[12:15], v[12:13], off
	v_lshl_add_u64 v[16:17], v[24:25], 0, v[140:141]
	v_mov_b32_e32 v143, v117
	global_load_dwordx4 v[16:19], v[16:17], off
	v_lshl_add_u64 v[20:21], v[28:29], 0, v[142:143]
	v_mov_b32_e32 v149, v117
	global_load_dwordx4 v[20:23], v[20:21], off
	v_lshl_add_u64 v[24:25], v[24:25], 0, v[148:149]
	v_mov_b32_e32 v151, v117
	global_load_dwordx4 v[24:27], v[24:25], off
	v_lshl_add_u64 v[28:29], v[28:29], 0, v[150:151]
	global_load_dwordx4 v[28:31], v[28:29], off
	s_add_i32 s18, s34, s33
	s_ashr_i32 s19, s18, 31
	s_lshl_b64 s[16:17], s[18:19], 2
	s_add_u32 s16, s46, s16
	s_addc_u32 s17, s47, s17
	s_lshl_b64 s[18:19], s[18:19], 13
	s_add_u32 s18, s48, s18
	s_addc_u32 s19, s49, s19
	v_lshlrev_b32_e32 v232, 1, v175
	v_lshlrev_b32_e32 v233, 1, v176
	global_load_ushort v230, v232, s[18:19]
	global_load_ushort v231, v233, s[18:19]
	s_waitcnt vmcnt(9)
	ds_write_b128 v115, v[0:3]
	s_waitcnt vmcnt(8)
	ds_write_b128 v168, v[4:7]
	s_waitcnt vmcnt(7)
	ds_write_b128 v169, v[8:11]
	s_waitcnt vmcnt(6)
	ds_write_b128 v170, v[12:15]
	s_waitcnt vmcnt(5)
	ds_write_b128 v171, v[16:19]
	s_waitcnt vmcnt(4)
	ds_write_b128 v172, v[20:23]
	s_waitcnt vmcnt(3)
	ds_write_b128 v173, v[24:27]
	s_waitcnt vmcnt(2)
	ds_write_b128 v174, v[28:31]
	s_waitcnt lgkmcnt(0)
	s_waitcnt vmcnt(1)
	v_and_b32_e32 v137, 0xfff, v230
	v_lshlrev_b32_e32 v232, 7, v137
	v_mov_b32_e32 v233, 0
	v_lshl_add_u64 v[4:5], v[156:157], 0, v[232:233]
	global_load_dwordx4 v[0:3], v[4:5], off
	s_nop 0
	global_load_dwordx4 v[4:7], v[4:5], off offset:64
	s_waitcnt vmcnt(2)
	v_and_b32_e32 v139, 0xfff, v231
	v_lshlrev_b32_e32 v232, 7, v139
	v_lshl_add_u64 v[12:13], v[156:157], 0, v[232:233]
	global_load_dwordx4 v[8:11], v[12:13], off
	s_nop 0
	global_load_dwordx4 v[12:15], v[12:13], off offset:64
	s_barrier
	global_load_dword v133, v117, s[16:17]
	s_waitcnt vmcnt(0)
	v_add_u32_e32 v232, 31, v133
	v_ashrrev_i32_e32 v135, 5, v232
	v_cmp_lt_i32_e32 vcc, v196, v135
	s_and_saveexec_b64 s[16:17], vcc
	s_cbranch_execz .LBB0_252
	v_cmp_lt_i32_e64 s[20:21], v175, v133
	v_cmp_lt_i32_e64 s[24:25], v176, v133
	s_mov_b64 s[22:23], 0
	v_mov_b32_e32 v143, v196
	v_mov_b32_e32 v141, v230
	v_mov_b32_e32 v149, v231
	s_branch .LBB0_258
